# attention tile loop unrolled by the K/V ring period (3) with one loop per wave type: ring offsets become constants, loop header and slot-select SALU removed (about 20 fewer instructions per tile per w
# speedup vs baseline: 1.0096x; 1.0096x over previous
.LBB0_228:
	s_and_b64 vcc, exec, s[16:17]
	s_cbranch_vccnz .LA1_top
.LB1_top:
	s_add_i32 s86, s65, -1
	s_cmp_ge_u32 s65, s66
	s_cbranch_scc1 .Lnod_b1
	s_add_i32 s4, s65, 1
	s_cmp_ge_u32 s4, s66
	s_cbranch_scc1 .Lnok_b1
	s_mov_b32 m0, s32
	s_nop 0
	global_load_lds_dwordx4 v128, s[80:81]
	s_add_i32 m0, m0, 0x2000
	s_nop 0
	global_load_lds_dwordx4 v129, s[80:81]
	s_cmp_eq_u32 s56, 0
	s_cbranch_scc0 .Ldk_b1
	s_mov_b32 m0, 0x4000
	s_nop 0
	global_load_lds_dwordx4 v132, s[80:81]
.Ldk_b1:
.Lnok_b1:
	s_add_i32 m0, s32, 0x12800
	s_nop 0
	global_load_lds_dwordx4 v130, s[80:81]
	s_add_i32 m0, m0, 0x2000
	s_nop 0
	global_load_lds_dwordx4 v131, s[80:81]
	s_cmp_eq_u32 s56, 0
	s_cbranch_scc1 .Ldv_b1
	s_cmp_gt_u32 s56, 4
	s_cbranch_scc1 .Ldv_b1
	s_add_i32 m0, s32, 0x16400
	s_nop 0
	global_load_lds_dwordx4 v132, s[80:81]

.Lwd_b1:
	s_barrier
	s_cmp_gt_i32 s86, s9
	s_cbranch_scc1 .LB1_end
	s_cmp_ge_i32 s86, s9
	s_cbranch_scc1 .LB1_pvonly
	v_add_u32_e32 v205, 0x5000, v165
	v_add_u32_e32 v206, 0x20400, v192
	ds_read_b64_tr_b16 v[96:97], v205 offset:34816
	ds_read_b64_tr_b16 v[98:99], v205 offset:37376
	ds_read_b64_tr_b16 v[100:101], v205 offset:39936
	ds_read_b64_tr_b16 v[102:103], v205 offset:42496
	ds_read_b64_tr_b16 v[104:105], v205 offset:45056
	ds_read_b64_tr_b16 v[106:107], v205 offset:47616
	ds_read_b64_tr_b16 v[108:109], v205 offset:50176
	ds_read_b64_tr_b16 v[110:111], v205 offset:52736
	ds_read_b64_tr_b16 v[176:177], v205 offset:34880
	ds_read_b64_tr_b16 v[178:179], v205 offset:37440
	ds_read_b64_tr_b16 v[180:181], v205 offset:40000
	ds_read_b64_tr_b16 v[182:183], v205 offset:42560
	ds_read_b64_tr_b16 v[184:185], v205 offset:45120
	ds_read_b64_tr_b16 v[186:187], v205 offset:47680
	s_setprio 1
	s_waitcnt lgkmcnt(12)
	v_mfma_f32_32x32x16_bf16 v[32:47], v[96:99], v[80:83], v[32:47]
	ds_read_b64_tr_b16 v[96:97], v205 offset:50240
	ds_read_b64_tr_b16 v[98:99], v205 offset:52800
	s_waitcnt lgkmcnt(12)
	v_mfma_f32_32x32x16_bf16 v[32:47], v[100:103], v[84:87], v[32:47]
	ds_read_b64_tr_b16 v[100:101], v205 offset:34944
	ds_read_b64_tr_b16 v[102:103], v205 offset:37504
	s_waitcnt lgkmcnt(12)
	v_mfma_f32_32x32x16_bf16 v[32:47], v[104:107], v[88:91], v[32:47]
	ds_read_b64_tr_b16 v[104:105], v205 offset:40064
	ds_read_b64_tr_b16 v[106:107], v205 offset:42624
	s_waitcnt lgkmcnt(12)
	v_mfma_f32_32x32x16_bf16 v[32:47], v[108:111], v[92:95], v[32:47]
	ds_read_b64_tr_b16 v[108:109], v205 offset:45184
	ds_read_b64_tr_b16 v[110:111], v205 offset:47744
	s_waitcnt lgkmcnt(12)
	v_mfma_f32_32x32x16_bf16 v[16:31], v[176:179], v[80:83], v[16:31]
	ds_read_b64_tr_b16 v[176:177], v205 offset:50304
	ds_read_b64_tr_b16 v[178:179], v205 offset:52864
	s_waitcnt lgkmcnt(12)
	v_mfma_f32_32x32x16_bf16 v[16:31], v[180:183], v[84:87], v[16:31]
	ds_read_b64_tr_b16 v[180:181], v205 offset:35008
	ds_read_b64_tr_b16 v[182:183], v205 offset:37568
	s_waitcnt lgkmcnt(12)
	v_mfma_f32_32x32x16_bf16 v[16:31], v[184:187], v[88:91], v[16:31]
	ds_read_b64_tr_b16 v[184:185], v205 offset:40128
	ds_read_b64_tr_b16 v[186:187], v205 offset:42688
	s_waitcnt lgkmcnt(12)
	v_mfma_f32_32x32x16_bf16 v[16:31], v[96:99], v[92:95], v[16:31]
	ds_read_b64_tr_b16 v[96:97], v205 offset:45248
	ds_read_b64_tr_b16 v[98:99], v205 offset:47808
	s_waitcnt lgkmcnt(12)
	v_mfma_f32_32x32x16_bf16 v[0:15], v[100:103], v[80:83], v[0:15]
	ds_read_b64_tr_b16 v[100:101], v205 offset:50368
	ds_read_b64_tr_b16 v[102:103], v205 offset:52928
	s_waitcnt lgkmcnt(12)
	v_mfma_f32_32x32x16_bf16 v[0:15], v[104:107], v[84:87], v[0:15]
	ds_read_b128 v[210:213], v206 offset:8704
	ds_read_b128 v[104:107], v206 offset:8736
	s_waitcnt lgkmcnt(12)
	v_mfma_f32_32x32x16_bf16 v[0:15], v[108:111], v[88:91], v[0:15]
	ds_read_b128 v[108:111], v206 offset:8768
	ds_read_b128 v[188:191], v206
	s_waitcnt lgkmcnt(12)
	v_mfma_f32_32x32x16_bf16 v[0:15], v[176:179], v[92:95], v[0:15]
	ds_read_b128 v[176:179], v206 offset:8800
	ds_read_b128 v[224:227], v206 offset:32
	s_waitcnt lgkmcnt(12)
	v_mfma_f32_32x32x16_bf16 v[48:63], v[180:183], v[80:83], v[48:63]
	ds_read_b128 v[228:231], v206 offset:64
	ds_read_b128 v[248:251], v206 offset:96
	s_waitcnt lgkmcnt(12)
	v_mfma_f32_32x32x16_bf16 v[48:63], v[184:187], v[84:87], v[48:63]
	s_waitcnt lgkmcnt(10)
	v_mfma_f32_32x32x16_bf16 v[48:63], v[96:99], v[88:91], v[48:63]
	s_waitcnt lgkmcnt(8)
	v_mfma_f32_32x32x16_bf16 v[48:63], v[100:103], v[92:95], v[48:63]
	s_waitcnt lgkmcnt(7)
	v_mfma_f32_32x32x16_bf16 v[80:95], v[210:213], v[112:115], v[64:79]
	s_waitcnt lgkmcnt(6)
	v_mfma_f32_32x32x16_bf16 v[80:95], v[104:107], v[116:119], v[80:95]
	s_waitcnt lgkmcnt(5)
	v_mfma_f32_32x32x16_bf16 v[80:95], v[108:111], v[120:123], v[80:95]
	s_waitcnt lgkmcnt(3)
	v_mfma_f32_32x32x16_bf16 v[80:95], v[176:179], v[124:127], v[80:95]
	s_waitcnt lgkmcnt(4)
	v_mfma_f32_32x32x16_bf16 v[96:111], v[188:191], v[112:115], v[64:79]
	s_waitcnt lgkmcnt(2)
	v_mfma_f32_32x32x16_bf16 v[96:111], v[224:227], v[116:119], v[96:111]
	s_waitcnt lgkmcnt(1)
	v_mfma_f32_32x32x16_bf16 v[96:111], v[228:231], v[120:123], v[96:111]
	s_waitcnt lgkmcnt(0)
	v_mfma_f32_32x32x16_bf16 v[96:111], v[248:251], v[124:127], v[96:111]
	s_setprio 0
	s_cmp_gt_i32 s33, 3
	s_cbranch_scc1 .LB1_end
	s_waitcnt lgkmcnt(0)
	s_add_i32 s4, s68, 0x100
	v_add_u32_e32 v205, s4, v204
	v_add_u32_e32 v176, 0x17d00, v205
	v_add_u32_e32 v178, 0x17d80, v205
	ds_read2_b32 v[176:177], v176 offset1:1
	ds_read2_b32 v[178:179], v178 offset1:1
	v_add_u32_e32 v180, 0x17d08, v205
	v_add_u32_e32 v182, 0x17d88, v205
	v_add_u32_e32 v184, 0x17d20, v205
	v_add_u32_e32 v186, 0x17da0, v205
	v_add_u32_e32 v188, 0x17d28, v205
	v_add_u32_e32 v190, 0x17da8, v205
	v_add_u32_e32 v206, 0x17d40, v205
	v_add_u32_e32 v210, 0x17dc0, v205
	v_add_u32_e32 v212, 0x17d48, v205
	v_add_u32_e32 v221, 0x17dc8, v205
	ds_read2_b32 v[180:181], v180 offset1:1
	ds_read2_b32 v[182:183], v182 offset1:1
	ds_read2_b32 v[184:185], v184 offset1:1
	ds_read2_b32 v[186:187], v186 offset1:1
	ds_read2_b32 v[188:189], v188 offset1:1
	ds_read2_b32 v[190:191], v190 offset1:1
	ds_read2_b32 v[206:207], v206 offset1:1
	ds_read2_b32 v[210:211], v210 offset1:1
	ds_read2_b32 v[212:213], v212 offset1:1
	ds_read2_b32 v[224:225], v221 offset1:1
	v_add_u32_e32 v221, 0x17d60, v205
	v_add_u32_e32 v223, 0x17de0, v205
	ds_read2_b32 v[226:227], v221 offset1:1
	ds_read2_b32 v[228:229], v223 offset1:1
	v_add_u32_e32 v221, 0x17d68, v205
	v_add_u32_e32 v205, 0x17de8, v205
	ds_read2_b32 v[230:231], v221 offset1:1
	s_waitcnt lgkmcnt(14)
	v_pk_add_f32 v[96:97], v[96:97], v[176:177]
	ds_read2_b32 v[176:177], v205 offset1:1
	s_waitcnt lgkmcnt(3)
	v_pk_add_f32 v[108:109], v[108:109], v[226:227]
	v_pk_add_f32 v[106:107], v[106:107], v[212:213]
	s_waitcnt lgkmcnt(1)
	v_pk_add_f32 v[110:111], v[110:111], v[230:231]
	v_pk_add_f32 v[104:105], v[104:105], v[206:207]
	v_pk_add_f32 v[102:103], v[102:103], v[188:189]
	v_pk_add_f32 v[100:101], v[100:101], v[184:185]
	v_pk_add_f32 v[98:99], v[98:99], v[180:181]
	s_waitcnt lgkmcnt(0)
	v_pk_add_f32 v[94:95], v[94:95], v[176:177]
	v_pk_add_f32 v[92:93], v[92:93], v[228:229]
	v_pk_add_f32 v[90:91], v[90:91], v[224:225]
	v_pk_add_f32 v[88:89], v[88:89], v[210:211]
	v_pk_add_f32 v[86:87], v[86:87], v[190:191]
	v_pk_add_f32 v[84:85], v[84:85], v[186:187]
	v_pk_add_f32 v[82:83], v[82:83], v[182:183]
	v_pk_add_f32 v[80:81], v[80:81], v[178:179]
	s_nop 0
.LB1_end:
	s_addk_i32 s68, 0x100
	s_add_i32 s65, s65, 1
	s_add_i32 s33, s33, -1
	v_lshl_add_u64 v[174:175], v[174:175], 0, s[78:79]
	s_cmp_eq_u32 s21, s68
	s_cbranch_scc1 .LB1_exit
.LB2_top:
	s_add_i32 s86, s65, -1
	s_cmp_ge_u32 s65, s66
	s_cbranch_scc1 .Lnod_b2
	s_add_i32 s4, s65, 1
	s_cmp_ge_u32 s4, s66
	s_cbranch_scc1 .Lnok_b2
	s_add_i32 m0, s32, 0x4400
	s_nop 0
	global_load_lds_dwordx4 v128, s[80:81]
	s_add_i32 m0, m0, 0x2000
	s_nop 0
	global_load_lds_dwordx4 v129, s[80:81]
	s_cmp_eq_u32 s56, 0
	s_cbranch_scc0 .Ldk_b2
	s_mov_b32 m0, 0x8400
	s_nop 0
	global_load_lds_dwordx4 v132, s[80:81]
.Ldk_b2:
.Lnok_b2:
	s_add_i32 m0, s32, 0x8800
	s_nop 0
	global_load_lds_dwordx4 v130, s[80:81]
	s_add_i32 m0, m0, 0x2000
	s_nop 0
	global_load_lds_dwordx4 v131, s[80:81]
	s_cmp_eq_u32 s56, 0
	s_cbranch_scc1 .Ldv_b2
	s_cmp_gt_u32 s56, 4
	s_cbranch_scc1 .Ldv_b2
	s_add_i32 m0, s32, 0xc400
	s_nop 0
	global_load_lds_dwordx4 v132, s[80:81]

.Lwd_b2:
	s_barrier
	s_cmp_gt_i32 s86, s9
	s_cbranch_scc1 .LB2_end
	s_cmp_ge_i32 s86, s9
	s_cbranch_scc1 .LB2_pvonly
	v_add_u32_e32 v205, 0xa000, v165
	v_add_u32_e32 v206, 0x0, v192
	ds_read_b64_tr_b16 v[96:97], v205 offset:34816
	ds_read_b64_tr_b16 v[98:99], v205 offset:37376
	ds_read_b64_tr_b16 v[100:101], v205 offset:39936
	ds_read_b64_tr_b16 v[102:103], v205 offset:42496
	ds_read_b64_tr_b16 v[104:105], v205 offset:45056
	ds_read_b64_tr_b16 v[106:107], v205 offset:47616
	ds_read_b64_tr_b16 v[108:109], v205 offset:50176
	ds_read_b64_tr_b16 v[110:111], v205 offset:52736
	ds_read_b64_tr_b16 v[176:177], v205 offset:34880
	ds_read_b64_tr_b16 v[178:179], v205 offset:37440
	ds_read_b64_tr_b16 v[180:181], v205 offset:40000
	ds_read_b64_tr_b16 v[182:183], v205 offset:42560
	ds_read_b64_tr_b16 v[184:185], v205 offset:45120
	ds_read_b64_tr_b16 v[186:187], v205 offset:47680
	s_setprio 1
	s_waitcnt lgkmcnt(12)
	v_mfma_f32_32x32x16_bf16 v[32:47], v[96:99], v[80:83], v[32:47]
	ds_read_b64_tr_b16 v[96:97], v205 offset:50240
	ds_read_b64_tr_b16 v[98:99], v205 offset:52800
	s_waitcnt lgkmcnt(12)
	v_mfma_f32_32x32x16_bf16 v[32:47], v[100:103], v[84:87], v[32:47]
	ds_read_b64_tr_b16 v[100:101], v205 offset:34944
	ds_read_b64_tr_b16 v[102:103], v205 offset:37504
	s_waitcnt lgkmcnt(12)
	v_mfma_f32_32x32x16_bf16 v[32:47], v[104:107], v[88:91], v[32:47]
	ds_read_b64_tr_b16 v[104:105], v205 offset:40064
	ds_read_b64_tr_b16 v[106:107], v205 offset:42624
	s_waitcnt lgkmcnt(12)
	v_mfma_f32_32x32x16_bf16 v[32:47], v[108:111], v[92:95], v[32:47]
	ds_read_b64_tr_b16 v[108:109], v205 offset:45184
	ds_read_b64_tr_b16 v[110:111], v205 offset:47744
	s_waitcnt lgkmcnt(12)
	v_mfma_f32_32x32x16_bf16 v[16:31], v[176:179], v[80:83], v[16:31]
	ds_read_b64_tr_b16 v[176:177], v205 offset:50304
	ds_read_b64_tr_b16 v[178:179], v205 offset:52864
	s_waitcnt lgkmcnt(12)
	v_mfma_f32_32x32x16_bf16 v[16:31], v[180:183], v[84:87], v[16:31]
	ds_read_b64_tr_b16 v[180:181], v205 offset:35008
	ds_read_b64_tr_b16 v[182:183], v205 offset:37568
	s_waitcnt lgkmcnt(12)
	v_mfma_f32_32x32x16_bf16 v[16:31], v[184:187], v[88:91], v[16:31]
	ds_read_b64_tr_b16 v[184:185], v205 offset:40128
	ds_read_b64_tr_b16 v[186:187], v205 offset:42688
	s_waitcnt lgkmcnt(12)
	v_mfma_f32_32x32x16_bf16 v[16:31], v[96:99], v[92:95], v[16:31]
	ds_read_b64_tr_b16 v[96:97], v205 offset:45248
	ds_read_b64_tr_b16 v[98:99], v205 offset:47808
	s_waitcnt lgkmcnt(12)
	v_mfma_f32_32x32x16_bf16 v[0:15], v[100:103], v[80:83], v[0:15]
	ds_read_b64_tr_b16 v[100:101], v205 offset:50368
	ds_read_b64_tr_b16 v[102:103], v205 offset:52928
	s_waitcnt lgkmcnt(12)
	v_mfma_f32_32x32x16_bf16 v[0:15], v[104:107], v[84:87], v[0:15]
	ds_read_b128 v[210:213], v206 offset:8704
	ds_read_b128 v[104:107], v206 offset:8736
	s_waitcnt lgkmcnt(12)
	v_mfma_f32_32x32x16_bf16 v[0:15], v[108:111], v[88:91], v[0:15]
	ds_read_b128 v[108:111], v206 offset:8768
	ds_read_b128 v[188:191], v206
	s_waitcnt lgkmcnt(12)
	v_mfma_f32_32x32x16_bf16 v[0:15], v[176:179], v[92:95], v[0:15]
	ds_read_b128 v[176:179], v206 offset:8800
	ds_read_b128 v[224:227], v206 offset:32
	s_waitcnt lgkmcnt(12)
	v_mfma_f32_32x32x16_bf16 v[48:63], v[180:183], v[80:83], v[48:63]
	ds_read_b128 v[228:231], v206 offset:64
	ds_read_b128 v[248:251], v206 offset:96
	s_waitcnt lgkmcnt(12)
	v_mfma_f32_32x32x16_bf16 v[48:63], v[184:187], v[84:87], v[48:63]
	s_waitcnt lgkmcnt(10)
	v_mfma_f32_32x32x16_bf16 v[48:63], v[96:99], v[88:91], v[48:63]
	s_waitcnt lgkmcnt(8)
	v_mfma_f32_32x32x16_bf16 v[48:63], v[100:103], v[92:95], v[48:63]
	s_waitcnt lgkmcnt(7)
	v_mfma_f32_32x32x16_bf16 v[80:95], v[210:213], v[112:115], v[64:79]
	s_waitcnt lgkmcnt(6)
	v_mfma_f32_32x32x16_bf16 v[80:95], v[104:107], v[116:119], v[80:95]
	s_waitcnt lgkmcnt(5)
	v_mfma_f32_32x32x16_bf16 v[80:95], v[108:111], v[120:123], v[80:95]
	s_waitcnt lgkmcnt(3)
	v_mfma_f32_32x32x16_bf16 v[80:95], v[176:179], v[124:127], v[80:95]
	s_waitcnt lgkmcnt(4)
	v_mfma_f32_32x32x16_bf16 v[96:111], v[188:191], v[112:115], v[64:79]
	s_waitcnt lgkmcnt(2)
	v_mfma_f32_32x32x16_bf16 v[96:111], v[224:227], v[116:119], v[96:111]
	s_waitcnt lgkmcnt(1)
	v_mfma_f32_32x32x16_bf16 v[96:111], v[228:231], v[120:123], v[96:111]
	s_waitcnt lgkmcnt(0)
	v_mfma_f32_32x32x16_bf16 v[96:111], v[248:251], v[124:127], v[96:111]
	s_setprio 0
	s_cmp_gt_i32 s33, 3
	s_cbranch_scc1 .LB2_end
	s_waitcnt lgkmcnt(0)
	s_add_i32 s4, s68, 0x100
	v_add_u32_e32 v205, s4, v204
	v_add_u32_e32 v176, 0x17d00, v205
	v_add_u32_e32 v178, 0x17d80, v205
	ds_read2_b32 v[176:177], v176 offset1:1
	ds_read2_b32 v[178:179], v178 offset1:1
	v_add_u32_e32 v180, 0x17d08, v205
	v_add_u32_e32 v182, 0x17d88, v205
	v_add_u32_e32 v184, 0x17d20, v205
	v_add_u32_e32 v186, 0x17da0, v205
	v_add_u32_e32 v188, 0x17d28, v205
	v_add_u32_e32 v190, 0x17da8, v205
	v_add_u32_e32 v206, 0x17d40, v205
	v_add_u32_e32 v210, 0x17dc0, v205
	v_add_u32_e32 v212, 0x17d48, v205
	v_add_u32_e32 v221, 0x17dc8, v205
	ds_read2_b32 v[180:181], v180 offset1:1
	ds_read2_b32 v[182:183], v182 offset1:1
	ds_read2_b32 v[184:185], v184 offset1:1
	ds_read2_b32 v[186:187], v186 offset1:1
	ds_read2_b32 v[188:189], v188 offset1:1
	ds_read2_b32 v[190:191], v190 offset1:1
	ds_read2_b32 v[206:207], v206 offset1:1
	ds_read2_b32 v[210:211], v210 offset1:1
	ds_read2_b32 v[212:213], v212 offset1:1
	ds_read2_b32 v[224:225], v221 offset1:1
	v_add_u32_e32 v221, 0x17d60, v205
	v_add_u32_e32 v223, 0x17de0, v205
	ds_read2_b32 v[226:227], v221 offset1:1
	ds_read2_b32 v[228:229], v223 offset1:1
	v_add_u32_e32 v221, 0x17d68, v205
	v_add_u32_e32 v205, 0x17de8, v205
	ds_read2_b32 v[230:231], v221 offset1:1
	s_waitcnt lgkmcnt(14)
	v_pk_add_f32 v[96:97], v[96:97], v[176:177]
	ds_read2_b32 v[176:177], v205 offset1:1
	s_waitcnt lgkmcnt(3)
	v_pk_add_f32 v[108:109], v[108:109], v[226:227]
	v_pk_add_f32 v[106:107], v[106:107], v[212:213]
	s_waitcnt lgkmcnt(1)
	v_pk_add_f32 v[110:111], v[110:111], v[230:231]
	v_pk_add_f32 v[104:105], v[104:105], v[206:207]
	v_pk_add_f32 v[102:103], v[102:103], v[188:189]
	v_pk_add_f32 v[100:101], v[100:101], v[184:185]
	v_pk_add_f32 v[98:99], v[98:99], v[180:181]
	s_waitcnt lgkmcnt(0)
	v_pk_add_f32 v[94:95], v[94:95], v[176:177]
	v_pk_add_f32 v[92:93], v[92:93], v[228:229]
	v_pk_add_f32 v[90:91], v[90:91], v[224:225]
	v_pk_add_f32 v[88:89], v[88:89], v[210:211]
	v_pk_add_f32 v[86:87], v[86:87], v[190:191]
	v_pk_add_f32 v[84:85], v[84:85], v[186:187]
	v_pk_add_f32 v[82:83], v[82:83], v[182:183]
	v_pk_add_f32 v[80:81], v[80:81], v[178:179]
	s_nop 0

.LB0_top:
	s_add_i32 s86, s65, -1
	s_cmp_ge_u32 s65, s66
	s_cbranch_scc1 .Lnod_b0
	s_add_i32 s4, s65, 1
	s_cmp_ge_u32 s4, s66
	s_cbranch_scc1 .Lnok_b0
	s_add_i32 m0, s32, 0x20400
	s_nop 0
	global_load_lds_dwordx4 v128, s[80:81]
	s_add_i32 m0, m0, 0x2000
	s_nop 0
	global_load_lds_dwordx4 v129, s[80:81]
	s_cmp_eq_u32 s56, 0
	s_cbranch_scc0 .Ldk_b0
	s_mov_b32 m0, 0x24400
	s_nop 0
	global_load_lds_dwordx4 v132, s[80:81]
.Ldk_b0:
.Lnok_b0:
	s_add_i32 m0, s32, 0xd800
	s_nop 0
	global_load_lds_dwordx4 v130, s[80:81]
	s_add_i32 m0, m0, 0x2000
	s_nop 0
	global_load_lds_dwordx4 v131, s[80:81]
	s_cmp_eq_u32 s56, 0
	s_cbranch_scc1 .Ldv_b0
	s_cmp_gt_u32 s56, 4
	s_cbranch_scc1 .Ldv_b0
	s_add_i32 m0, s32, 0x11400
	s_nop 0
	global_load_lds_dwordx4 v132, s[80:81]

.Lwd_b0:
	s_barrier
	s_cmp_gt_i32 s86, s9
	s_cbranch_scc1 .LB0_end
	s_cmp_ge_i32 s86, s9
	s_cbranch_scc1 .LB0_pvonly
	v_add_u32_e32 v205, 0x0, v165
	v_add_u32_e32 v206, 0x4400, v192
	ds_read_b64_tr_b16 v[96:97], v205 offset:34816
	ds_read_b64_tr_b16 v[98:99], v205 offset:37376
	ds_read_b64_tr_b16 v[100:101], v205 offset:39936
	ds_read_b64_tr_b16 v[102:103], v205 offset:42496
	ds_read_b64_tr_b16 v[104:105], v205 offset:45056
	ds_read_b64_tr_b16 v[106:107], v205 offset:47616
	ds_read_b64_tr_b16 v[108:109], v205 offset:50176
	ds_read_b64_tr_b16 v[110:111], v205 offset:52736
	ds_read_b64_tr_b16 v[176:177], v205 offset:34880
	ds_read_b64_tr_b16 v[178:179], v205 offset:37440
	ds_read_b64_tr_b16 v[180:181], v205 offset:40000
	ds_read_b64_tr_b16 v[182:183], v205 offset:42560
	ds_read_b64_tr_b16 v[184:185], v205 offset:45120
	ds_read_b64_tr_b16 v[186:187], v205 offset:47680
	s_setprio 1
	s_waitcnt lgkmcnt(12)
	v_mfma_f32_32x32x16_bf16 v[32:47], v[96:99], v[80:83], v[32:47]
	ds_read_b64_tr_b16 v[96:97], v205 offset:50240
	ds_read_b64_tr_b16 v[98:99], v205 offset:52800
	s_waitcnt lgkmcnt(12)
	v_mfma_f32_32x32x16_bf16 v[32:47], v[100:103], v[84:87], v[32:47]
	ds_read_b64_tr_b16 v[100:101], v205 offset:34944
	ds_read_b64_tr_b16 v[102:103], v205 offset:37504
	s_waitcnt lgkmcnt(12)
	v_mfma_f32_32x32x16_bf16 v[32:47], v[104:107], v[88:91], v[32:47]
	ds_read_b64_tr_b16 v[104:105], v205 offset:40064
	ds_read_b64_tr_b16 v[106:107], v205 offset:42624
	s_waitcnt lgkmcnt(12)
	v_mfma_f32_32x32x16_bf16 v[32:47], v[108:111], v[92:95], v[32:47]
	ds_read_b64_tr_b16 v[108:109], v205 offset:45184
	ds_read_b64_tr_b16 v[110:111], v205 offset:47744
	s_waitcnt lgkmcnt(12)
	v_mfma_f32_32x32x16_bf16 v[16:31], v[176:179], v[80:83], v[16:31]
	ds_read_b64_tr_b16 v[176:177], v205 offset:50304
	ds_read_b64_tr_b16 v[178:179], v205 offset:52864
	s_waitcnt lgkmcnt(12)
	v_mfma_f32_32x32x16_bf16 v[16:31], v[180:183], v[84:87], v[16:31]
	ds_read_b64_tr_b16 v[180:181], v205 offset:35008
	ds_read_b64_tr_b16 v[182:183], v205 offset:37568
	s_waitcnt lgkmcnt(12)
	v_mfma_f32_32x32x16_bf16 v[16:31], v[184:187], v[88:91], v[16:31]
	ds_read_b64_tr_b16 v[184:185], v205 offset:40128
	ds_read_b64_tr_b16 v[186:187], v205 offset:42688
	s_waitcnt lgkmcnt(12)
	v_mfma_f32_32x32x16_bf16 v[16:31], v[96:99], v[92:95], v[16:31]
	ds_read_b64_tr_b16 v[96:97], v205 offset:45248
	ds_read_b64_tr_b16 v[98:99], v205 offset:47808
	s_waitcnt lgkmcnt(12)
	v_mfma_f32_32x32x16_bf16 v[0:15], v[100:103], v[80:83], v[0:15]
	ds_read_b64_tr_b16 v[100:101], v205 offset:50368
	ds_read_b64_tr_b16 v[102:103], v205 offset:52928
	s_waitcnt lgkmcnt(12)
	v_mfma_f32_32x32x16_bf16 v[0:15], v[104:107], v[84:87], v[0:15]
	ds_read_b128 v[210:213], v206 offset:8704
	ds_read_b128 v[104:107], v206 offset:8736
	s_waitcnt lgkmcnt(12)
	v_mfma_f32_32x32x16_bf16 v[0:15], v[108:111], v[88:91], v[0:15]
	ds_read_b128 v[108:111], v206 offset:8768
	ds_read_b128 v[188:191], v206
	s_waitcnt lgkmcnt(12)
	v_mfma_f32_32x32x16_bf16 v[0:15], v[176:179], v[92:95], v[0:15]
	ds_read_b128 v[176:179], v206 offset:8800
	ds_read_b128 v[224:227], v206 offset:32
	s_waitcnt lgkmcnt(12)
	v_mfma_f32_32x32x16_bf16 v[48:63], v[180:183], v[80:83], v[48:63]
	ds_read_b128 v[228:231], v206 offset:64
	ds_read_b128 v[248:251], v206 offset:96
	s_waitcnt lgkmcnt(12)
	v_mfma_f32_32x32x16_bf16 v[48:63], v[184:187], v[84:87], v[48:63]
	s_waitcnt lgkmcnt(10)
	v_mfma_f32_32x32x16_bf16 v[48:63], v[96:99], v[88:91], v[48:63]
	s_waitcnt lgkmcnt(8)
	v_mfma_f32_32x32x16_bf16 v[48:63], v[100:103], v[92:95], v[48:63]
	s_waitcnt lgkmcnt(7)
	v_mfma_f32_32x32x16_bf16 v[80:95], v[210:213], v[112:115], v[64:79]
	s_waitcnt lgkmcnt(6)
	v_mfma_f32_32x32x16_bf16 v[80:95], v[104:107], v[116:119], v[80:95]
	s_waitcnt lgkmcnt(5)
	v_mfma_f32_32x32x16_bf16 v[80:95], v[108:111], v[120:123], v[80:95]
	s_waitcnt lgkmcnt(3)
	v_mfma_f32_32x32x16_bf16 v[80:95], v[176:179], v[124:127], v[80:95]
	s_waitcnt lgkmcnt(4)
	v_mfma_f32_32x32x16_bf16 v[96:111], v[188:191], v[112:115], v[64:79]
	s_waitcnt lgkmcnt(2)
	v_mfma_f32_32x32x16_bf16 v[96:111], v[224:227], v[116:119], v[96:111]
	s_waitcnt lgkmcnt(1)
	v_mfma_f32_32x32x16_bf16 v[96:111], v[228:231], v[120:123], v[96:111]
	s_waitcnt lgkmcnt(0)
	v_mfma_f32_32x32x16_bf16 v[96:111], v[248:251], v[124:127], v[96:111]
	s_setprio 0
	s_cmp_gt_i32 s33, 3
	s_cbranch_scc1 .LB0_end
	s_waitcnt lgkmcnt(0)
	s_add_i32 s4, s68, 0x100
	v_add_u32_e32 v205, s4, v204
	v_add_u32_e32 v176, 0x17d00, v205
	v_add_u32_e32 v178, 0x17d80, v205
	ds_read2_b32 v[176:177], v176 offset1:1
	ds_read2_b32 v[178:179], v178 offset1:1
	v_add_u32_e32 v180, 0x17d08, v205
	v_add_u32_e32 v182, 0x17d88, v205
	v_add_u32_e32 v184, 0x17d20, v205
	v_add_u32_e32 v186, 0x17da0, v205
	v_add_u32_e32 v188, 0x17d28, v205
	v_add_u32_e32 v190, 0x17da8, v205
	v_add_u32_e32 v206, 0x17d40, v205
	v_add_u32_e32 v210, 0x17dc0, v205
	v_add_u32_e32 v212, 0x17d48, v205
	v_add_u32_e32 v221, 0x17dc8, v205
	ds_read2_b32 v[180:181], v180 offset1:1
	ds_read2_b32 v[182:183], v182 offset1:1
	ds_read2_b32 v[184:185], v184 offset1:1
	ds_read2_b32 v[186:187], v186 offset1:1
	ds_read2_b32 v[188:189], v188 offset1:1
	ds_read2_b32 v[190:191], v190 offset1:1
	ds_read2_b32 v[206:207], v206 offset1:1
	ds_read2_b32 v[210:211], v210 offset1:1
	ds_read2_b32 v[212:213], v212 offset1:1
	ds_read2_b32 v[224:225], v221 offset1:1
	v_add_u32_e32 v221, 0x17d60, v205
	v_add_u32_e32 v223, 0x17de0, v205
	ds_read2_b32 v[226:227], v221 offset1:1
	ds_read2_b32 v[228:229], v223 offset1:1
	v_add_u32_e32 v221, 0x17d68, v205
	v_add_u32_e32 v205, 0x17de8, v205
	ds_read2_b32 v[230:231], v221 offset1:1
	s_waitcnt lgkmcnt(14)
	v_pk_add_f32 v[96:97], v[96:97], v[176:177]
	ds_read2_b32 v[176:177], v205 offset1:1
	s_waitcnt lgkmcnt(3)
	v_pk_add_f32 v[108:109], v[108:109], v[226:227]
	v_pk_add_f32 v[106:107], v[106:107], v[212:213]
	s_waitcnt lgkmcnt(1)
	v_pk_add_f32 v[110:111], v[110:111], v[230:231]
	v_pk_add_f32 v[104:105], v[104:105], v[206:207]
	v_pk_add_f32 v[102:103], v[102:103], v[188:189]
	v_pk_add_f32 v[100:101], v[100:101], v[184:185]
	v_pk_add_f32 v[98:99], v[98:99], v[180:181]
	s_waitcnt lgkmcnt(0)
	v_pk_add_f32 v[94:95], v[94:95], v[176:177]
	v_pk_add_f32 v[92:93], v[92:93], v[228:229]
	v_pk_add_f32 v[90:91], v[90:91], v[224:225]
	v_pk_add_f32 v[88:89], v[88:89], v[210:211]
	v_pk_add_f32 v[86:87], v[86:87], v[190:191]
	v_pk_add_f32 v[84:85], v[84:85], v[186:187]
	v_pk_add_f32 v[82:83], v[82:83], v[182:183]
	v_pk_add_f32 v[80:81], v[80:81], v[178:179]
	s_nop 0
.LB0_end:
	s_addk_i32 s68, 0x100
	s_add_i32 s65, s65, 1
	s_add_i32 s33, s33, -1
	v_lshl_add_u64 v[174:175], v[174:175], 0, s[78:79]
	s_cmp_eq_u32 s21, s68
	s_cbranch_scc1 .LB0_exit
	s_branch .LB1_top
.LB1_pvonly:
	s_mov_b32 s69, 1
	s_mul_i32 s4, s69, 0x5000
	v_add_u32_e32 v205, s4, v165
	ds_read_b64_tr_b16 v[224:225], v205 offset:34816
	ds_read_b64_tr_b16 v[226:227], v205 offset:37376
	ds_read_b64_tr_b16 v[228:229], v205 offset:39936
	ds_read_b64_tr_b16 v[230:231], v205 offset:42496
	ds_read_b64_tr_b16 v[248:249], v205 offset:45056
	ds_read_b64_tr_b16 v[250:251], v205 offset:47616
	ds_read_b64_tr_b16 v[210:211], v205 offset:50176
	ds_read_b64_tr_b16 v[212:213], v205 offset:52736
	s_setprio 1
	s_waitcnt lgkmcnt(6)
	v_mfma_f32_32x32x16_bf16 v[32:47], v[224:227], v[80:83], v[32:47]
	s_setprio 0
	ds_read_b64_tr_b16 v[224:225], v205 offset:34880
	ds_read_b64_tr_b16 v[226:227], v205 offset:37440
	s_setprio 1
	s_waitcnt lgkmcnt(6)
	v_mfma_f32_32x32x16_bf16 v[32:47], v[228:231], v[84:87], v[32:47]
	s_setprio 0
	ds_read_b64_tr_b16 v[228:229], v205 offset:40000
	ds_read_b64_tr_b16 v[230:231], v205 offset:42560
	s_setprio 1
	s_waitcnt lgkmcnt(6)
	v_mfma_f32_32x32x16_bf16 v[32:47], v[248:251], v[88:91], v[32:47]
	s_setprio 0
	ds_read_b64_tr_b16 v[248:249], v205 offset:45120
	ds_read_b64_tr_b16 v[250:251], v205 offset:47680
	s_setprio 1
	s_waitcnt lgkmcnt(6)
	v_mfma_f32_32x32x16_bf16 v[32:47], v[210:213], v[92:95], v[32:47]
	s_setprio 0
	ds_read_b64_tr_b16 v[210:211], v205 offset:50240
	ds_read_b64_tr_b16 v[212:213], v205 offset:52800
	s_setprio 1
	s_waitcnt lgkmcnt(6)
	v_mfma_f32_32x32x16_bf16 v[16:31], v[224:227], v[80:83], v[16:31]
	s_setprio 0
	ds_read_b64_tr_b16 v[224:225], v205 offset:34944
	ds_read_b64_tr_b16 v[226:227], v205 offset:37504
	s_setprio 1
	s_waitcnt lgkmcnt(6)
	v_mfma_f32_32x32x16_bf16 v[16:31], v[228:231], v[84:87], v[16:31]
	s_setprio 0
	ds_read_b64_tr_b16 v[228:229], v205 offset:40064
	ds_read_b64_tr_b16 v[230:231], v205 offset:42624
	s_setprio 1
	s_waitcnt lgkmcnt(6)
	v_mfma_f32_32x32x16_bf16 v[16:31], v[248:251], v[88:91], v[16:31]
	s_setprio 0
	ds_read_b64_tr_b16 v[248:249], v205 offset:45184
	ds_read_b64_tr_b16 v[250:251], v205 offset:47744
	s_setprio 1
	s_waitcnt lgkmcnt(6)
	v_mfma_f32_32x32x16_bf16 v[16:31], v[210:213], v[92:95], v[16:31]
	s_setprio 0
	ds_read_b64_tr_b16 v[210:211], v205 offset:50304
	ds_read_b64_tr_b16 v[212:213], v205 offset:52864
	s_setprio 1
	s_waitcnt lgkmcnt(6)
	v_mfma_f32_32x32x16_bf16 v[0:15], v[224:227], v[80:83], v[0:15]
	s_setprio 0
	ds_read_b64_tr_b16 v[224:225], v205 offset:35008
	ds_read_b64_tr_b16 v[226:227], v205 offset:37568
	s_setprio 1
	s_waitcnt lgkmcnt(6)
	v_mfma_f32_32x32x16_bf16 v[0:15], v[228:231], v[84:87], v[0:15]
	s_setprio 0
	ds_read_b64_tr_b16 v[228:229], v205 offset:40128
	ds_read_b64_tr_b16 v[230:231], v205 offset:42688
	s_setprio 1
	s_waitcnt lgkmcnt(6)
	v_mfma_f32_32x32x16_bf16 v[0:15], v[248:251], v[88:91], v[0:15]
	s_setprio 0
	ds_read_b64_tr_b16 v[248:249], v205 offset:45248
	ds_read_b64_tr_b16 v[250:251], v205 offset:47808
	s_setprio 1
	s_waitcnt lgkmcnt(6)
	v_mfma_f32_32x32x16_bf16 v[0:15], v[210:213], v[92:95], v[0:15]
	s_setprio 0
	ds_read_b64_tr_b16 v[210:211], v205 offset:50368
	ds_read_b64_tr_b16 v[212:213], v205 offset:52928
	s_setprio 1
	s_waitcnt lgkmcnt(6)
	v_mfma_f32_32x32x16_bf16 v[48:63], v[224:227], v[80:83], v[48:63]
	s_setprio 0
	s_setprio 1
	s_waitcnt lgkmcnt(4)
	v_mfma_f32_32x32x16_bf16 v[48:63], v[228:231], v[84:87], v[48:63]
	s_setprio 0
	s_setprio 1
	s_waitcnt lgkmcnt(2)
	v_mfma_f32_32x32x16_bf16 v[48:63], v[248:251], v[88:91], v[48:63]
	s_setprio 0
	s_setprio 1
	s_waitcnt lgkmcnt(0)
	v_mfma_f32_32x32x16_bf16 v[48:63], v[210:213], v[92:95], v[48:63]
	s_setprio 0
	s_branch .LB1_end
.LB1_exit:
	s_mov_b32 s69, 1
	s_branch .LBB0_243
.LB2_pvonly:
	s_mov_b32 s69, 2
	s_mul_i32 s4, s69, 0x5000
	v_add_u32_e32 v205, s4, v165
	ds_read_b64_tr_b16 v[224:225], v205 offset:34816
	ds_read_b64_tr_b16 v[226:227], v205 offset:37376
	ds_read_b64_tr_b16 v[228:229], v205 offset:39936
	ds_read_b64_tr_b16 v[230:231], v205 offset:42496
	ds_read_b64_tr_b16 v[248:249], v205 offset:45056
	ds_read_b64_tr_b16 v[250:251], v205 offset:47616
	ds_read_b64_tr_b16 v[210:211], v205 offset:50176
	ds_read_b64_tr_b16 v[212:213], v205 offset:52736
	s_setprio 1
	s_waitcnt lgkmcnt(6)
	v_mfma_f32_32x32x16_bf16 v[32:47], v[224:227], v[80:83], v[32:47]
	s_setprio 0
	ds_read_b64_tr_b16 v[224:225], v205 offset:34880
	ds_read_b64_tr_b16 v[226:227], v205 offset:37440
	s_setprio 1
	s_waitcnt lgkmcnt(6)
	v_mfma_f32_32x32x16_bf16 v[32:47], v[228:231], v[84:87], v[32:47]
	s_setprio 0
	ds_read_b64_tr_b16 v[228:229], v205 offset:40000
	ds_read_b64_tr_b16 v[230:231], v205 offset:42560
	s_setprio 1
	s_waitcnt lgkmcnt(6)
	v_mfma_f32_32x32x16_bf16 v[32:47], v[248:251], v[88:91], v[32:47]
	s_setprio 0
	ds_read_b64_tr_b16 v[248:249], v205 offset:45120
	ds_read_b64_tr_b16 v[250:251], v205 offset:47680
	s_setprio 1
	s_waitcnt lgkmcnt(6)
	v_mfma_f32_32x32x16_bf16 v[32:47], v[210:213], v[92:95], v[32:47]
	s_setprio 0
	ds_read_b64_tr_b16 v[210:211], v205 offset:50240
	ds_read_b64_tr_b16 v[212:213], v205 offset:52800
	s_setprio 1
	s_waitcnt lgkmcnt(6)
	v_mfma_f32_32x32x16_bf16 v[16:31], v[224:227], v[80:83], v[16:31]
	s_setprio 0
	ds_read_b64_tr_b16 v[224:225], v205 offset:34944
	ds_read_b64_tr_b16 v[226:227], v205 offset:37504
	s_setprio 1
	s_waitcnt lgkmcnt(6)
	v_mfma_f32_32x32x16_bf16 v[16:31], v[228:231], v[84:87], v[16:31]
	s_setprio 0
	ds_read_b64_tr_b16 v[228:229], v205 offset:40064
	ds_read_b64_tr_b16 v[230:231], v205 offset:42624
	s_setprio 1
	s_waitcnt lgkmcnt(6)
	v_mfma_f32_32x32x16_bf16 v[16:31], v[248:251], v[88:91], v[16:31]
	s_setprio 0
	ds_read_b64_tr_b16 v[248:249], v205 offset:45184
	ds_read_b64_tr_b16 v[250:251], v205 offset:47744
	s_setprio 1
	s_waitcnt lgkmcnt(6)
	v_mfma_f32_32x32x16_bf16 v[16:31], v[210:213], v[92:95], v[16:31]
	s_setprio 0
	ds_read_b64_tr_b16 v[210:211], v205 offset:50304
	ds_read_b64_tr_b16 v[212:213], v205 offset:52864
	s_setprio 1
	s_waitcnt lgkmcnt(6)
	v_mfma_f32_32x32x16_bf16 v[0:15], v[224:227], v[80:83], v[0:15]
	s_setprio 0
	ds_read_b64_tr_b16 v[224:225], v205 offset:35008
	ds_read_b64_tr_b16 v[226:227], v205 offset:37568
	s_setprio 1
	s_waitcnt lgkmcnt(6)
	v_mfma_f32_32x32x16_bf16 v[0:15], v[228:231], v[84:87], v[0:15]
	s_setprio 0
	ds_read_b64_tr_b16 v[228:229], v205 offset:40128
	ds_read_b64_tr_b16 v[230:231], v205 offset:42688
	s_setprio 1
	s_waitcnt lgkmcnt(6)
	v_mfma_f32_32x32x16_bf16 v[0:15], v[248:251], v[88:91], v[0:15]
	s_setprio 0
	ds_read_b64_tr_b16 v[248:249], v205 offset:45248
	ds_read_b64_tr_b16 v[250:251], v205 offset:47808
	s_setprio 1
	s_waitcnt lgkmcnt(6)
	v_mfma_f32_32x32x16_bf16 v[0:15], v[210:213], v[92:95], v[0:15]
	s_setprio 0
	ds_read_b64_tr_b16 v[210:211], v205 offset:50368
	ds_read_b64_tr_b16 v[212:213], v205 offset:52928
	s_setprio 1
	s_waitcnt lgkmcnt(6)
	v_mfma_f32_32x32x16_bf16 v[48:63], v[224:227], v[80:83], v[48:63]
	s_setprio 0
	s_setprio 1
	s_waitcnt lgkmcnt(4)
	v_mfma_f32_32x32x16_bf16 v[48:63], v[228:231], v[84:87], v[48:63]
	s_setprio 0
	s_setprio 1
	s_waitcnt lgkmcnt(2)
	v_mfma_f32_32x32x16_bf16 v[48:63], v[248:251], v[88:91], v[48:63]
	s_setprio 0
	s_setprio 1
	s_waitcnt lgkmcnt(0)
	v_mfma_f32_32x32x16_bf16 v[48:63], v[210:213], v[92:95], v[48:63]
	s_setprio 0
	s_branch .LB2_end
.LB2_exit:
	s_mov_b32 s69, 2
	s_branch .LBB0_243
.LB0_pvonly:
	s_mov_b32 s69, 0
	s_mul_i32 s4, s69, 0x5000
	v_add_u32_e32 v205, s4, v165
	ds_read_b64_tr_b16 v[224:225], v205 offset:34816
	ds_read_b64_tr_b16 v[226:227], v205 offset:37376
	ds_read_b64_tr_b16 v[228:229], v205 offset:39936
	ds_read_b64_tr_b16 v[230:231], v205 offset:42496
	ds_read_b64_tr_b16 v[248:249], v205 offset:45056
	ds_read_b64_tr_b16 v[250:251], v205 offset:47616
	ds_read_b64_tr_b16 v[210:211], v205 offset:50176
	ds_read_b64_tr_b16 v[212:213], v205 offset:52736
	s_setprio 1
	s_waitcnt lgkmcnt(6)
	v_mfma_f32_32x32x16_bf16 v[32:47], v[224:227], v[80:83], v[32:47]
	s_setprio 0
	ds_read_b64_tr_b16 v[224:225], v205 offset:34880
	ds_read_b64_tr_b16 v[226:227], v205 offset:37440
	s_setprio 1
	s_waitcnt lgkmcnt(6)
	v_mfma_f32_32x32x16_bf16 v[32:47], v[228:231], v[84:87], v[32:47]
	s_setprio 0
	ds_read_b64_tr_b16 v[228:229], v205 offset:40000
	ds_read_b64_tr_b16 v[230:231], v205 offset:42560
	s_setprio 1
	s_waitcnt lgkmcnt(6)
	v_mfma_f32_32x32x16_bf16 v[32:47], v[248:251], v[88:91], v[32:47]
	s_setprio 0
	ds_read_b64_tr_b16 v[248:249], v205 offset:45120
	ds_read_b64_tr_b16 v[250:251], v205 offset:47680
	s_setprio 1
	s_waitcnt lgkmcnt(6)
	v_mfma_f32_32x32x16_bf16 v[32:47], v[210:213], v[92:95], v[32:47]
	s_setprio 0
	ds_read_b64_tr_b16 v[210:211], v205 offset:50240
	ds_read_b64_tr_b16 v[212:213], v205 offset:52800
	s_setprio 1
	s_waitcnt lgkmcnt(6)
	v_mfma_f32_32x32x16_bf16 v[16:31], v[224:227], v[80:83], v[16:31]
	s_setprio 0
	ds_read_b64_tr_b16 v[224:225], v205 offset:34944
	ds_read_b64_tr_b16 v[226:227], v205 offset:37504
	s_setprio 1
	s_waitcnt lgkmcnt(6)
	v_mfma_f32_32x32x16_bf16 v[16:31], v[228:231], v[84:87], v[16:31]
	s_setprio 0
	ds_read_b64_tr_b16 v[228:229], v205 offset:40064
	ds_read_b64_tr_b16 v[230:231], v205 offset:42624
	s_setprio 1
	s_waitcnt lgkmcnt(6)
	v_mfma_f32_32x32x16_bf16 v[16:31], v[248:251], v[88:91], v[16:31]
	s_setprio 0
	ds_read_b64_tr_b16 v[248:249], v205 offset:45184
	ds_read_b64_tr_b16 v[250:251], v205 offset:47744
	s_setprio 1
	s_waitcnt lgkmcnt(6)
	v_mfma_f32_32x32x16_bf16 v[16:31], v[210:213], v[92:95], v[16:31]
	s_setprio 0
	ds_read_b64_tr_b16 v[210:211], v205 offset:50304
	ds_read_b64_tr_b16 v[212:213], v205 offset:52864
	s_setprio 1
	s_waitcnt lgkmcnt(6)
	v_mfma_f32_32x32x16_bf16 v[0:15], v[224:227], v[80:83], v[0:15]
	s_setprio 0
	ds_read_b64_tr_b16 v[224:225], v205 offset:35008
	ds_read_b64_tr_b16 v[226:227], v205 offset:37568
	s_setprio 1
	s_waitcnt lgkmcnt(6)
	v_mfma_f32_32x32x16_bf16 v[0:15], v[228:231], v[84:87], v[0:15]
	s_setprio 0
	ds_read_b64_tr_b16 v[228:229], v205 offset:40128
	ds_read_b64_tr_b16 v[230:231], v205 offset:42688
	s_setprio 1
	s_waitcnt lgkmcnt(6)
	v_mfma_f32_32x32x16_bf16 v[0:15], v[248:251], v[88:91], v[0:15]
	s_setprio 0
	ds_read_b64_tr_b16 v[248:249], v205 offset:45248
	ds_read_b64_tr_b16 v[250:251], v205 offset:47808
	s_setprio 1
	s_waitcnt lgkmcnt(6)
	v_mfma_f32_32x32x16_bf16 v[0:15], v[210:213], v[92:95], v[0:15]
	s_setprio 0
	ds_read_b64_tr_b16 v[210:211], v205 offset:50368
	ds_read_b64_tr_b16 v[212:213], v205 offset:52928
	s_setprio 1
	s_waitcnt lgkmcnt(6)
	v_mfma_f32_32x32x16_bf16 v[48:63], v[224:227], v[80:83], v[48:63]
	s_setprio 0
	s_setprio 1
	s_waitcnt lgkmcnt(4)
	v_mfma_f32_32x32x16_bf16 v[48:63], v[228:231], v[84:87], v[48:63]
	s_setprio 0
	s_setprio 1
	s_waitcnt lgkmcnt(2)
	v_mfma_f32_32x32x16_bf16 v[48:63], v[248:251], v[88:91], v[48:63]
	s_setprio 0
	s_setprio 1
	s_waitcnt lgkmcnt(0)
	v_mfma_f32_32x32x16_bf16 v[48:63], v[210:213], v[92:95], v[48:63]
	s_setprio 0
	s_branch .LB0_end
.LB0_exit:
	s_mov_b32 s69, 0
	s_branch .LBB0_243
.LA1_top:
	v_add_u32_e32 v205, 0x0, v165
	v_add_u32_e32 v206, 0x4400, v192
	ds_read_b64_tr_b16 v[96:97], v205 offset:34816
	ds_read_b64_tr_b16 v[98:99], v205 offset:37376
	ds_read_b64_tr_b16 v[100:101], v205 offset:39936
	ds_read_b64_tr_b16 v[102:103], v205 offset:42496
	ds_read_b64_tr_b16 v[104:105], v205 offset:45056
	ds_read_b64_tr_b16 v[106:107], v205 offset:47616
	ds_read_b64_tr_b16 v[108:109], v205 offset:50176
	ds_read_b64_tr_b16 v[110:111], v205 offset:52736
	ds_read_b64_tr_b16 v[176:177], v205 offset:34880
	ds_read_b64_tr_b16 v[178:179], v205 offset:37440
	ds_read_b64_tr_b16 v[180:181], v205 offset:40000
	ds_read_b64_tr_b16 v[182:183], v205 offset:42560
	ds_read_b64_tr_b16 v[184:185], v205 offset:45120
	ds_read_b64_tr_b16 v[186:187], v205 offset:47680
	s_setprio 1
	s_waitcnt lgkmcnt(12)
	v_mfma_f32_32x32x16_bf16 v[32:47], v[96:99], v[80:83], v[32:47]
	ds_read_b64_tr_b16 v[96:97], v205 offset:50240
	ds_read_b64_tr_b16 v[98:99], v205 offset:52800
	s_waitcnt lgkmcnt(12)
	v_mfma_f32_32x32x16_bf16 v[32:47], v[100:103], v[84:87], v[32:47]
	ds_read_b64_tr_b16 v[100:101], v205 offset:34944
	ds_read_b64_tr_b16 v[102:103], v205 offset:37504
	s_waitcnt lgkmcnt(12)
	v_mfma_f32_32x32x16_bf16 v[32:47], v[104:107], v[88:91], v[32:47]
	ds_read_b64_tr_b16 v[104:105], v205 offset:40064
	ds_read_b64_tr_b16 v[106:107], v205 offset:42624
	s_waitcnt lgkmcnt(12)
	v_mfma_f32_32x32x16_bf16 v[32:47], v[108:111], v[92:95], v[32:47]
	ds_read_b64_tr_b16 v[108:109], v205 offset:45184
	ds_read_b64_tr_b16 v[110:111], v205 offset:47744
	s_waitcnt lgkmcnt(12)
	v_mfma_f32_32x32x16_bf16 v[16:31], v[176:179], v[80:83], v[16:31]
	ds_read_b64_tr_b16 v[176:177], v205 offset:50304
	ds_read_b64_tr_b16 v[178:179], v205 offset:52864
	s_waitcnt lgkmcnt(12)
	v_mfma_f32_32x32x16_bf16 v[16:31], v[180:183], v[84:87], v[16:31]
	ds_read_b64_tr_b16 v[180:181], v205 offset:35008
	ds_read_b64_tr_b16 v[182:183], v205 offset:37568
	s_waitcnt lgkmcnt(12)
	v_mfma_f32_32x32x16_bf16 v[16:31], v[184:187], v[88:91], v[16:31]
	ds_read_b64_tr_b16 v[184:185], v205 offset:40128
	ds_read_b64_tr_b16 v[186:187], v205 offset:42688
	s_waitcnt lgkmcnt(12)
	v_mfma_f32_32x32x16_bf16 v[16:31], v[96:99], v[92:95], v[16:31]
	ds_read_b64_tr_b16 v[96:97], v205 offset:45248
	ds_read_b64_tr_b16 v[98:99], v205 offset:47808
	s_waitcnt lgkmcnt(12)
	v_mfma_f32_32x32x16_bf16 v[0:15], v[100:103], v[80:83], v[0:15]
	ds_read_b64_tr_b16 v[100:101], v205 offset:50368
	ds_read_b64_tr_b16 v[102:103], v205 offset:52928
	s_waitcnt lgkmcnt(12)
	v_mfma_f32_32x32x16_bf16 v[0:15], v[104:107], v[84:87], v[0:15]
	ds_read_b128 v[210:213], v206 offset:8704
	ds_read_b128 v[104:107], v206 offset:8736
	s_waitcnt lgkmcnt(12)
	v_mfma_f32_32x32x16_bf16 v[0:15], v[108:111], v[88:91], v[0:15]
	ds_read_b128 v[108:111], v206 offset:8768
	ds_read_b128 v[188:191], v206
	s_waitcnt lgkmcnt(12)
	v_mfma_f32_32x32x16_bf16 v[0:15], v[176:179], v[92:95], v[0:15]
	ds_read_b128 v[176:179], v206 offset:8800
	ds_read_b128 v[224:227], v206 offset:32
	s_waitcnt lgkmcnt(12)
	v_mfma_f32_32x32x16_bf16 v[48:63], v[180:183], v[80:83], v[48:63]
	ds_read_b128 v[228:231], v206 offset:64
	ds_read_b128 v[248:251], v206 offset:96
	s_waitcnt lgkmcnt(12)
	v_mfma_f32_32x32x16_bf16 v[48:63], v[184:187], v[84:87], v[48:63]
	s_waitcnt lgkmcnt(10)
	v_mfma_f32_32x32x16_bf16 v[48:63], v[96:99], v[88:91], v[48:63]
	s_waitcnt lgkmcnt(8)
	v_mfma_f32_32x32x16_bf16 v[48:63], v[100:103], v[92:95], v[48:63]
	s_waitcnt lgkmcnt(7)
	v_mfma_f32_32x32x16_bf16 v[80:95], v[210:213], v[112:115], v[64:79]
	s_waitcnt lgkmcnt(6)
	v_mfma_f32_32x32x16_bf16 v[80:95], v[104:107], v[116:119], v[80:95]
	s_waitcnt lgkmcnt(5)
	v_mfma_f32_32x32x16_bf16 v[80:95], v[108:111], v[120:123], v[80:95]
	s_waitcnt lgkmcnt(3)
	v_mfma_f32_32x32x16_bf16 v[80:95], v[176:179], v[124:127], v[80:95]
	s_waitcnt lgkmcnt(4)
	v_mfma_f32_32x32x16_bf16 v[96:111], v[188:191], v[112:115], v[64:79]
	s_waitcnt lgkmcnt(2)
	v_mfma_f32_32x32x16_bf16 v[96:111], v[224:227], v[116:119], v[96:111]
	s_waitcnt lgkmcnt(1)
	v_mfma_f32_32x32x16_bf16 v[96:111], v[228:231], v[120:123], v[96:111]
	s_waitcnt lgkmcnt(0)
	v_mfma_f32_32x32x16_bf16 v[96:111], v[248:251], v[124:127], v[96:111]
	s_setprio 0
	s_cmp_gt_i32 s33, 2
	s_cbranch_scc1 .Latt_a1_stg
	s_waitcnt lgkmcnt(0)
	v_add_u32_e32 v205, s68, v204
	v_add_u32_e32 v176, 0x17d00, v205
	v_add_u32_e32 v178, 0x17d80, v205
	ds_read2_b32 v[176:177], v176 offset1:1
	ds_read2_b32 v[178:179], v178 offset1:1
	v_add_u32_e32 v180, 0x17d08, v205
	v_add_u32_e32 v182, 0x17d88, v205
	v_add_u32_e32 v184, 0x17d20, v205
	v_add_u32_e32 v186, 0x17da0, v205
	v_add_u32_e32 v188, 0x17d28, v205
	v_add_u32_e32 v190, 0x17da8, v205
	v_add_u32_e32 v206, 0x17d40, v205
	v_add_u32_e32 v210, 0x17dc0, v205
	v_add_u32_e32 v212, 0x17d48, v205
	v_add_u32_e32 v221, 0x17dc8, v205
	ds_read2_b32 v[180:181], v180 offset1:1
	ds_read2_b32 v[182:183], v182 offset1:1
	ds_read2_b32 v[184:185], v184 offset1:1
	ds_read2_b32 v[186:187], v186 offset1:1
	ds_read2_b32 v[188:189], v188 offset1:1
	ds_read2_b32 v[190:191], v190 offset1:1
	ds_read2_b32 v[206:207], v206 offset1:1
	ds_read2_b32 v[210:211], v210 offset1:1
	ds_read2_b32 v[212:213], v212 offset1:1
	ds_read2_b32 v[224:225], v221 offset1:1
	v_add_u32_e32 v221, 0x17d60, v205
	v_add_u32_e32 v223, 0x17de0, v205
	ds_read2_b32 v[226:227], v221 offset1:1
	ds_read2_b32 v[228:229], v223 offset1:1
	v_add_u32_e32 v221, 0x17d68, v205
	v_add_u32_e32 v205, 0x17de8, v205
	ds_read2_b32 v[230:231], v221 offset1:1
	s_waitcnt lgkmcnt(14)
	v_pk_add_f32 v[96:97], v[96:97], v[176:177]
	ds_read2_b32 v[176:177], v205 offset1:1
	s_waitcnt lgkmcnt(3)
	v_pk_add_f32 v[108:109], v[108:109], v[226:227]
	v_pk_add_f32 v[106:107], v[106:107], v[212:213]
	s_waitcnt lgkmcnt(1)
	v_pk_add_f32 v[110:111], v[110:111], v[230:231]
	v_pk_add_f32 v[104:105], v[104:105], v[206:207]
	v_pk_add_f32 v[102:103], v[102:103], v[188:189]
	v_pk_add_f32 v[100:101], v[100:101], v[184:185]
	v_pk_add_f32 v[98:99], v[98:99], v[180:181]
	s_waitcnt lgkmcnt(0)
	v_pk_add_f32 v[94:95], v[94:95], v[176:177]
	v_pk_add_f32 v[92:93], v[92:93], v[228:229]
	v_pk_add_f32 v[90:91], v[90:91], v[224:225]
	v_pk_add_f32 v[88:89], v[88:89], v[210:211]
	v_pk_add_f32 v[86:87], v[86:87], v[190:191]
	v_pk_add_f32 v[84:85], v[84:85], v[186:187]
	v_pk_add_f32 v[82:83], v[82:83], v[182:183]
	v_pk_add_f32 v[80:81], v[80:81], v[178:179]
	s_nop 0

.Lwd_a1:
	s_barrier
	s_add_i32 s4, s65, 1
	s_cmp_ge_u32 s4, s66
	s_cbranch_scc1 .Lnod_a1
	s_add_i32 s4, s65, 2
	s_cmp_ge_u32 s4, s66
	s_cbranch_scc1 .Lnok_a1
	s_add_i32 m0, s32, 0x4400
	s_nop 0
	global_load_lds_dwordx4 v128, s[80:81]
	s_add_i32 m0, m0, 0x2000
	s_nop 0
	global_load_lds_dwordx4 v129, s[80:81]
	s_cmp_eq_u32 s56, 0
	s_cbranch_scc0 .Ldk_a1
	s_mov_b32 m0, 0x8400
	s_nop 0
	global_load_lds_dwordx4 v132, s[80:81]

.LA2_top:
	v_add_u32_e32 v205, 0x5000, v165
	v_add_u32_e32 v206, 0x20400, v192
	ds_read_b64_tr_b16 v[96:97], v205 offset:34816
	ds_read_b64_tr_b16 v[98:99], v205 offset:37376
	ds_read_b64_tr_b16 v[100:101], v205 offset:39936
	ds_read_b64_tr_b16 v[102:103], v205 offset:42496
	ds_read_b64_tr_b16 v[104:105], v205 offset:45056
	ds_read_b64_tr_b16 v[106:107], v205 offset:47616
	ds_read_b64_tr_b16 v[108:109], v205 offset:50176
	ds_read_b64_tr_b16 v[110:111], v205 offset:52736
	ds_read_b64_tr_b16 v[176:177], v205 offset:34880
	ds_read_b64_tr_b16 v[178:179], v205 offset:37440
	ds_read_b64_tr_b16 v[180:181], v205 offset:40000
	ds_read_b64_tr_b16 v[182:183], v205 offset:42560
	ds_read_b64_tr_b16 v[184:185], v205 offset:45120
	ds_read_b64_tr_b16 v[186:187], v205 offset:47680
	s_setprio 1
	s_waitcnt lgkmcnt(12)
	v_mfma_f32_32x32x16_bf16 v[32:47], v[96:99], v[80:83], v[32:47]
	ds_read_b64_tr_b16 v[96:97], v205 offset:50240
	ds_read_b64_tr_b16 v[98:99], v205 offset:52800
	s_waitcnt lgkmcnt(12)
	v_mfma_f32_32x32x16_bf16 v[32:47], v[100:103], v[84:87], v[32:47]
	ds_read_b64_tr_b16 v[100:101], v205 offset:34944
	ds_read_b64_tr_b16 v[102:103], v205 offset:37504
	s_waitcnt lgkmcnt(12)
	v_mfma_f32_32x32x16_bf16 v[32:47], v[104:107], v[88:91], v[32:47]
	ds_read_b64_tr_b16 v[104:105], v205 offset:40064
	ds_read_b64_tr_b16 v[106:107], v205 offset:42624
	s_waitcnt lgkmcnt(12)
	v_mfma_f32_32x32x16_bf16 v[32:47], v[108:111], v[92:95], v[32:47]
	ds_read_b64_tr_b16 v[108:109], v205 offset:45184
	ds_read_b64_tr_b16 v[110:111], v205 offset:47744
	s_waitcnt lgkmcnt(12)
	v_mfma_f32_32x32x16_bf16 v[16:31], v[176:179], v[80:83], v[16:31]
	ds_read_b64_tr_b16 v[176:177], v205 offset:50304
	ds_read_b64_tr_b16 v[178:179], v205 offset:52864
	s_waitcnt lgkmcnt(12)
	v_mfma_f32_32x32x16_bf16 v[16:31], v[180:183], v[84:87], v[16:31]
	ds_read_b64_tr_b16 v[180:181], v205 offset:35008
	ds_read_b64_tr_b16 v[182:183], v205 offset:37568
	s_waitcnt lgkmcnt(12)
	v_mfma_f32_32x32x16_bf16 v[16:31], v[184:187], v[88:91], v[16:31]
	ds_read_b64_tr_b16 v[184:185], v205 offset:40128
	ds_read_b64_tr_b16 v[186:187], v205 offset:42688
	s_waitcnt lgkmcnt(12)
	v_mfma_f32_32x32x16_bf16 v[16:31], v[96:99], v[92:95], v[16:31]
	ds_read_b64_tr_b16 v[96:97], v205 offset:45248
	ds_read_b64_tr_b16 v[98:99], v205 offset:47808
	s_waitcnt lgkmcnt(12)
	v_mfma_f32_32x32x16_bf16 v[0:15], v[100:103], v[80:83], v[0:15]
	ds_read_b64_tr_b16 v[100:101], v205 offset:50368
	ds_read_b64_tr_b16 v[102:103], v205 offset:52928
	s_waitcnt lgkmcnt(12)
	v_mfma_f32_32x32x16_bf16 v[0:15], v[104:107], v[84:87], v[0:15]
	ds_read_b128 v[210:213], v206 offset:8704
	ds_read_b128 v[104:107], v206 offset:8736
	s_waitcnt lgkmcnt(12)
	v_mfma_f32_32x32x16_bf16 v[0:15], v[108:111], v[88:91], v[0:15]
	ds_read_b128 v[108:111], v206 offset:8768
	ds_read_b128 v[188:191], v206
	s_waitcnt lgkmcnt(12)
	v_mfma_f32_32x32x16_bf16 v[0:15], v[176:179], v[92:95], v[0:15]
	ds_read_b128 v[176:179], v206 offset:8800
	ds_read_b128 v[224:227], v206 offset:32
	s_waitcnt lgkmcnt(12)
	v_mfma_f32_32x32x16_bf16 v[48:63], v[180:183], v[80:83], v[48:63]
	ds_read_b128 v[228:231], v206 offset:64
	ds_read_b128 v[248:251], v206 offset:96
	s_waitcnt lgkmcnt(12)
	v_mfma_f32_32x32x16_bf16 v[48:63], v[184:187], v[84:87], v[48:63]
	s_waitcnt lgkmcnt(10)
	v_mfma_f32_32x32x16_bf16 v[48:63], v[96:99], v[88:91], v[48:63]
	s_waitcnt lgkmcnt(8)
	v_mfma_f32_32x32x16_bf16 v[48:63], v[100:103], v[92:95], v[48:63]
	s_waitcnt lgkmcnt(7)
	v_mfma_f32_32x32x16_bf16 v[80:95], v[210:213], v[112:115], v[64:79]
	s_waitcnt lgkmcnt(6)
	v_mfma_f32_32x32x16_bf16 v[80:95], v[104:107], v[116:119], v[80:95]
	s_waitcnt lgkmcnt(5)
	v_mfma_f32_32x32x16_bf16 v[80:95], v[108:111], v[120:123], v[80:95]
	s_waitcnt lgkmcnt(3)
	v_mfma_f32_32x32x16_bf16 v[80:95], v[176:179], v[124:127], v[80:95]
	s_waitcnt lgkmcnt(4)
	v_mfma_f32_32x32x16_bf16 v[96:111], v[188:191], v[112:115], v[64:79]
	s_waitcnt lgkmcnt(2)
	v_mfma_f32_32x32x16_bf16 v[96:111], v[224:227], v[116:119], v[96:111]
	s_waitcnt lgkmcnt(1)
	v_mfma_f32_32x32x16_bf16 v[96:111], v[228:231], v[120:123], v[96:111]
	s_waitcnt lgkmcnt(0)
	v_mfma_f32_32x32x16_bf16 v[96:111], v[248:251], v[124:127], v[96:111]
	s_setprio 0
	s_cmp_gt_i32 s33, 2
	s_cbranch_scc1 .Latt_a2_stg
	s_waitcnt lgkmcnt(0)
	v_add_u32_e32 v205, s68, v204
	v_add_u32_e32 v176, 0x17d00, v205
	v_add_u32_e32 v178, 0x17d80, v205
	ds_read2_b32 v[176:177], v176 offset1:1
	ds_read2_b32 v[178:179], v178 offset1:1
	v_add_u32_e32 v180, 0x17d08, v205
	v_add_u32_e32 v182, 0x17d88, v205
	v_add_u32_e32 v184, 0x17d20, v205
	v_add_u32_e32 v186, 0x17da0, v205
	v_add_u32_e32 v188, 0x17d28, v205
	v_add_u32_e32 v190, 0x17da8, v205
	v_add_u32_e32 v206, 0x17d40, v205
	v_add_u32_e32 v210, 0x17dc0, v205
	v_add_u32_e32 v212, 0x17d48, v205
	v_add_u32_e32 v221, 0x17dc8, v205
	ds_read2_b32 v[180:181], v180 offset1:1
	ds_read2_b32 v[182:183], v182 offset1:1
	ds_read2_b32 v[184:185], v184 offset1:1
	ds_read2_b32 v[186:187], v186 offset1:1
	ds_read2_b32 v[188:189], v188 offset1:1
	ds_read2_b32 v[190:191], v190 offset1:1
	ds_read2_b32 v[206:207], v206 offset1:1
	ds_read2_b32 v[210:211], v210 offset1:1
	ds_read2_b32 v[212:213], v212 offset1:1
	ds_read2_b32 v[224:225], v221 offset1:1
	v_add_u32_e32 v221, 0x17d60, v205
	v_add_u32_e32 v223, 0x17de0, v205
	ds_read2_b32 v[226:227], v221 offset1:1
	ds_read2_b32 v[228:229], v223 offset1:1
	v_add_u32_e32 v221, 0x17d68, v205
	v_add_u32_e32 v205, 0x17de8, v205
	ds_read2_b32 v[230:231], v221 offset1:1
	s_waitcnt lgkmcnt(14)
	v_pk_add_f32 v[96:97], v[96:97], v[176:177]
	ds_read2_b32 v[176:177], v205 offset1:1
	s_waitcnt lgkmcnt(3)
	v_pk_add_f32 v[108:109], v[108:109], v[226:227]
	v_pk_add_f32 v[106:107], v[106:107], v[212:213]
	s_waitcnt lgkmcnt(1)
	v_pk_add_f32 v[110:111], v[110:111], v[230:231]
	v_pk_add_f32 v[104:105], v[104:105], v[206:207]
	v_pk_add_f32 v[102:103], v[102:103], v[188:189]
	v_pk_add_f32 v[100:101], v[100:101], v[184:185]
	v_pk_add_f32 v[98:99], v[98:99], v[180:181]
	s_waitcnt lgkmcnt(0)
	v_pk_add_f32 v[94:95], v[94:95], v[176:177]
	v_pk_add_f32 v[92:93], v[92:93], v[228:229]
	v_pk_add_f32 v[90:91], v[90:91], v[224:225]
	v_pk_add_f32 v[88:89], v[88:89], v[210:211]
	v_pk_add_f32 v[86:87], v[86:87], v[190:191]
	v_pk_add_f32 v[84:85], v[84:85], v[186:187]
	v_pk_add_f32 v[82:83], v[82:83], v[182:183]
	v_pk_add_f32 v[80:81], v[80:81], v[178:179]
	s_nop 0

.Lwd_a2:
	s_barrier
	s_add_i32 s4, s65, 1
	s_cmp_ge_u32 s4, s66
	s_cbranch_scc1 .Lnod_a2
	s_add_i32 s4, s65, 2
	s_cmp_ge_u32 s4, s66
	s_cbranch_scc1 .Lnok_a2
	s_add_i32 m0, s32, 0x20400
	s_nop 0
	global_load_lds_dwordx4 v128, s[80:81]
	s_add_i32 m0, m0, 0x2000
	s_nop 0
	global_load_lds_dwordx4 v129, s[80:81]
	s_cmp_eq_u32 s56, 0
	s_cbranch_scc0 .Ldk_a2
	s_mov_b32 m0, 0x24400
	s_nop 0
	global_load_lds_dwordx4 v132, s[80:81]

.LA0_top:
	v_add_u32_e32 v205, 0xa000, v165
	v_add_u32_e32 v206, 0x0, v192
	ds_read_b64_tr_b16 v[96:97], v205 offset:34816
	ds_read_b64_tr_b16 v[98:99], v205 offset:37376
	ds_read_b64_tr_b16 v[100:101], v205 offset:39936
	ds_read_b64_tr_b16 v[102:103], v205 offset:42496
	ds_read_b64_tr_b16 v[104:105], v205 offset:45056
	ds_read_b64_tr_b16 v[106:107], v205 offset:47616
	ds_read_b64_tr_b16 v[108:109], v205 offset:50176
	ds_read_b64_tr_b16 v[110:111], v205 offset:52736
	ds_read_b64_tr_b16 v[176:177], v205 offset:34880
	ds_read_b64_tr_b16 v[178:179], v205 offset:37440
	ds_read_b64_tr_b16 v[180:181], v205 offset:40000
	ds_read_b64_tr_b16 v[182:183], v205 offset:42560
	ds_read_b64_tr_b16 v[184:185], v205 offset:45120
	ds_read_b64_tr_b16 v[186:187], v205 offset:47680
	s_setprio 1
	s_waitcnt lgkmcnt(12)
	v_mfma_f32_32x32x16_bf16 v[32:47], v[96:99], v[80:83], v[32:47]
	ds_read_b64_tr_b16 v[96:97], v205 offset:50240
	ds_read_b64_tr_b16 v[98:99], v205 offset:52800
	s_waitcnt lgkmcnt(12)
	v_mfma_f32_32x32x16_bf16 v[32:47], v[100:103], v[84:87], v[32:47]
	ds_read_b64_tr_b16 v[100:101], v205 offset:34944
	ds_read_b64_tr_b16 v[102:103], v205 offset:37504
	s_waitcnt lgkmcnt(12)
	v_mfma_f32_32x32x16_bf16 v[32:47], v[104:107], v[88:91], v[32:47]
	ds_read_b64_tr_b16 v[104:105], v205 offset:40064
	ds_read_b64_tr_b16 v[106:107], v205 offset:42624
	s_waitcnt lgkmcnt(12)
	v_mfma_f32_32x32x16_bf16 v[32:47], v[108:111], v[92:95], v[32:47]
	ds_read_b64_tr_b16 v[108:109], v205 offset:45184
	ds_read_b64_tr_b16 v[110:111], v205 offset:47744
	s_waitcnt lgkmcnt(12)
	v_mfma_f32_32x32x16_bf16 v[16:31], v[176:179], v[80:83], v[16:31]
	ds_read_b64_tr_b16 v[176:177], v205 offset:50304
	ds_read_b64_tr_b16 v[178:179], v205 offset:52864
	s_waitcnt lgkmcnt(12)
	v_mfma_f32_32x32x16_bf16 v[16:31], v[180:183], v[84:87], v[16:31]
	ds_read_b64_tr_b16 v[180:181], v205 offset:35008
	ds_read_b64_tr_b16 v[182:183], v205 offset:37568
	s_waitcnt lgkmcnt(12)
	v_mfma_f32_32x32x16_bf16 v[16:31], v[184:187], v[88:91], v[16:31]
	ds_read_b64_tr_b16 v[184:185], v205 offset:40128
	ds_read_b64_tr_b16 v[186:187], v205 offset:42688
	s_waitcnt lgkmcnt(12)
	v_mfma_f32_32x32x16_bf16 v[16:31], v[96:99], v[92:95], v[16:31]
	ds_read_b64_tr_b16 v[96:97], v205 offset:45248
	ds_read_b64_tr_b16 v[98:99], v205 offset:47808
	s_waitcnt lgkmcnt(12)
	v_mfma_f32_32x32x16_bf16 v[0:15], v[100:103], v[80:83], v[0:15]
	ds_read_b64_tr_b16 v[100:101], v205 offset:50368
	ds_read_b64_tr_b16 v[102:103], v205 offset:52928
	s_waitcnt lgkmcnt(12)
	v_mfma_f32_32x32x16_bf16 v[0:15], v[104:107], v[84:87], v[0:15]
	ds_read_b128 v[210:213], v206 offset:8704
	ds_read_b128 v[104:107], v206 offset:8736
	s_waitcnt lgkmcnt(12)
	v_mfma_f32_32x32x16_bf16 v[0:15], v[108:111], v[88:91], v[0:15]
	ds_read_b128 v[108:111], v206 offset:8768
	ds_read_b128 v[188:191], v206
	s_waitcnt lgkmcnt(12)
	v_mfma_f32_32x32x16_bf16 v[0:15], v[176:179], v[92:95], v[0:15]
	ds_read_b128 v[176:179], v206 offset:8800
	ds_read_b128 v[224:227], v206 offset:32
	s_waitcnt lgkmcnt(12)
	v_mfma_f32_32x32x16_bf16 v[48:63], v[180:183], v[80:83], v[48:63]
	ds_read_b128 v[228:231], v206 offset:64
	ds_read_b128 v[248:251], v206 offset:96
	s_waitcnt lgkmcnt(12)
	v_mfma_f32_32x32x16_bf16 v[48:63], v[184:187], v[84:87], v[48:63]
	s_waitcnt lgkmcnt(10)
	v_mfma_f32_32x32x16_bf16 v[48:63], v[96:99], v[88:91], v[48:63]
	s_waitcnt lgkmcnt(8)
	v_mfma_f32_32x32x16_bf16 v[48:63], v[100:103], v[92:95], v[48:63]
	s_waitcnt lgkmcnt(7)
	v_mfma_f32_32x32x16_bf16 v[80:95], v[210:213], v[112:115], v[64:79]
	s_waitcnt lgkmcnt(6)
	v_mfma_f32_32x32x16_bf16 v[80:95], v[104:107], v[116:119], v[80:95]
	s_waitcnt lgkmcnt(5)
	v_mfma_f32_32x32x16_bf16 v[80:95], v[108:111], v[120:123], v[80:95]
	s_waitcnt lgkmcnt(3)
	v_mfma_f32_32x32x16_bf16 v[80:95], v[176:179], v[124:127], v[80:95]
	s_waitcnt lgkmcnt(4)
	v_mfma_f32_32x32x16_bf16 v[96:111], v[188:191], v[112:115], v[64:79]
	s_waitcnt lgkmcnt(2)
	v_mfma_f32_32x32x16_bf16 v[96:111], v[224:227], v[116:119], v[96:111]
	s_waitcnt lgkmcnt(1)
	v_mfma_f32_32x32x16_bf16 v[96:111], v[228:231], v[120:123], v[96:111]
	s_waitcnt lgkmcnt(0)
	v_mfma_f32_32x32x16_bf16 v[96:111], v[248:251], v[124:127], v[96:111]
	s_setprio 0
	s_cmp_gt_i32 s33, 2
	s_cbranch_scc1 .Latt_a0_stg
	s_waitcnt lgkmcnt(0)
	v_add_u32_e32 v205, s68, v204
	v_add_u32_e32 v176, 0x17d00, v205
	v_add_u32_e32 v178, 0x17d80, v205
	ds_read2_b32 v[176:177], v176 offset1:1
	ds_read2_b32 v[178:179], v178 offset1:1
	v_add_u32_e32 v180, 0x17d08, v205
	v_add_u32_e32 v182, 0x17d88, v205
	v_add_u32_e32 v184, 0x17d20, v205
	v_add_u32_e32 v186, 0x17da0, v205
	v_add_u32_e32 v188, 0x17d28, v205
	v_add_u32_e32 v190, 0x17da8, v205
	v_add_u32_e32 v206, 0x17d40, v205
	v_add_u32_e32 v210, 0x17dc0, v205
	v_add_u32_e32 v212, 0x17d48, v205
	v_add_u32_e32 v221, 0x17dc8, v205
	ds_read2_b32 v[180:181], v180 offset1:1
	ds_read2_b32 v[182:183], v182 offset1:1
	ds_read2_b32 v[184:185], v184 offset1:1
	ds_read2_b32 v[186:187], v186 offset1:1
	ds_read2_b32 v[188:189], v188 offset1:1
	ds_read2_b32 v[190:191], v190 offset1:1
	ds_read2_b32 v[206:207], v206 offset1:1
	ds_read2_b32 v[210:211], v210 offset1:1
	ds_read2_b32 v[212:213], v212 offset1:1
	ds_read2_b32 v[224:225], v221 offset1:1
	v_add_u32_e32 v221, 0x17d60, v205
	v_add_u32_e32 v223, 0x17de0, v205
	ds_read2_b32 v[226:227], v221 offset1:1
	ds_read2_b32 v[228:229], v223 offset1:1
	v_add_u32_e32 v221, 0x17d68, v205
	v_add_u32_e32 v205, 0x17de8, v205
	ds_read2_b32 v[230:231], v221 offset1:1
	s_waitcnt lgkmcnt(14)
	v_pk_add_f32 v[96:97], v[96:97], v[176:177]
	ds_read2_b32 v[176:177], v205 offset1:1
	s_waitcnt lgkmcnt(3)
	v_pk_add_f32 v[108:109], v[108:109], v[226:227]
	v_pk_add_f32 v[106:107], v[106:107], v[212:213]
	s_waitcnt lgkmcnt(1)
	v_pk_add_f32 v[110:111], v[110:111], v[230:231]
	v_pk_add_f32 v[104:105], v[104:105], v[206:207]
	v_pk_add_f32 v[102:103], v[102:103], v[188:189]
	v_pk_add_f32 v[100:101], v[100:101], v[184:185]
	v_pk_add_f32 v[98:99], v[98:99], v[180:181]
	s_waitcnt lgkmcnt(0)
	v_pk_add_f32 v[94:95], v[94:95], v[176:177]
	v_pk_add_f32 v[92:93], v[92:93], v[228:229]
	v_pk_add_f32 v[90:91], v[90:91], v[224:225]
	v_pk_add_f32 v[88:89], v[88:89], v[210:211]
	v_pk_add_f32 v[86:87], v[86:87], v[190:191]
	v_pk_add_f32 v[84:85], v[84:85], v[186:187]
	v_pk_add_f32 v[82:83], v[82:83], v[182:183]
	v_pk_add_f32 v[80:81], v[80:81], v[178:179]
	s_nop 0

.Lwd_a0:
	s_barrier
	s_add_i32 s4, s65, 1
	s_cmp_ge_u32 s4, s66
	s_cbranch_scc1 .Lnod_a0
	s_add_i32 s4, s65, 2
	s_cmp_ge_u32 s4, s66
	s_cbranch_scc1 .Lnok_a0
	s_mov_b32 m0, s32
	s_nop 0
	global_load_lds_dwordx4 v128, s[80:81]
	s_add_i32 m0, m0, 0x2000
	s_nop 0
	global_load_lds_dwordx4 v129, s[80:81]
	s_cmp_eq_u32 s56, 0
	s_cbranch_scc0 .Ldk_a0
	s_mov_b32 m0, 0x4000
	s_nop 0
	global_load_lds_dwordx4 v132, s[80:81]
